# DKVQ epilogue: remaining ssq butterfly ds_bpermute pairs (lane^16, lane^32) -> permlane16/32_swap
# speedup vs baseline: 1.0081x; 1.0015x over previous
.LBB0_590:
	v_mul_f32_e32 v161, v173, v173
	v_mul_f32_e32 v163, v169, v169
	v_fmac_f32_e32 v161, v172, v172
	v_fmac_f32_e32 v163, v168, v168
	v_add_f32_e32 v161, v161, v163
	v_mul_f32_e32 v163, v171, v171
	v_mul_f32_e32 v165, v167, v167
	v_fmac_f32_e32 v163, v170, v170
	v_fmac_f32_e32 v165, v166, v166
	v_add_f32_e32 v163, v163, v165
	v_add_f32_e32 v161, v161, v163
	v_mul_f32_e32 v163, v195, v195
	v_mul_f32_e32 v165, v177, v177
	v_fmac_f32_e32 v163, v194, v194
	v_fmac_f32_e32 v165, v176, v176
	v_add_f32_e32 v163, v163, v165
	v_mul_f32_e32 v165, v179, v179
	v_mul_f32_e32 v166, v175, v175
	v_fmac_f32_e32 v165, v178, v178
	v_fmac_f32_e32 v166, v174, v174
	v_add_f32_e32 v165, v165, v166
	v_add_f32_e32 v163, v163, v165
	v_add_f32_e32 v161, v161, v163
	v_mov_b32_e32 v163, v161
	v_mov_b32_e32 v251, v161
	s_nop 1
	v_permlane16_swap_b32_e32 v163, v251
	s_waitcnt lgkmcnt(0)
	v_add_f32_e32 v161, v163, v251
	v_mov_b32_e32 v163, v161
	v_mov_b32_e32 v251, v161
	s_nop 1
	v_permlane32_swap_b32_e32 v163, v251
	s_and_saveexec_b64 s[0:1], s[40:41]
	s_cbranch_execz .LBB0_592
	v_lshlrev_b64 v[166:167], 5, v[130:131]
	v_lshl_add_u64 v[166:167], s[34:35], 0, v[166:167]
	v_lshl_add_u64 v[166:167], s[46:47], 2, v[166:167]
	s_lshl_b32 s64, s62, 2
	v_lshl_add_u64 v[166:167], v[166:167], 0, s[64:65]
	s_waitcnt lgkmcnt(0)
	v_add_f32_e32 v161, v163, v251
	global_store_dword v[166:167], v161, off

.LBB0_593:
	s_and_b64 vcc, exec, s[16:17]
	s_cbranch_vccz .LBB0_597
	s_waitcnt lgkmcnt(7)
	v_pk_mul_f32 v[126:127], v[126:127], v[164:165] op_sel_hi:[1,0]
	v_pk_mul_f32 v[124:125], v[124:125], v[164:165] op_sel_hi:[1,0]
	v_pk_mul_f32 v[168:169], v[122:123], v[164:165] op_sel_hi:[1,0]
	v_pk_mul_f32 v[122:123], v[120:121], v[164:165] op_sel_hi:[1,0]
	v_mul_f32_e32 v120, v125, v125
	v_mul_f32_e32 v121, v127, v127
	v_fmac_f32_e32 v120, v124, v124
	v_fmac_f32_e32 v121, v126, v126
	v_add_f32_e32 v120, v120, v121
	v_mul_f32_e32 v121, v123, v123
	v_mul_f32_e32 v161, v169, v169
	v_fmac_f32_e32 v121, v122, v122
	v_fmac_f32_e32 v161, v168, v168
	v_add_f32_e32 v121, v121, v161
	v_pk_mul_f32 v[118:119], v[118:119], v[164:165] op_sel_hi:[1,0]
	v_pk_mul_f32 v[116:117], v[116:117], v[164:165] op_sel_hi:[1,0]
	v_add_f32_e32 v161, v120, v121
	v_cvt_pk_bf16_f32 v121, v126, v127
	v_pk_mul_f32 v[126:127], v[112:113], v[164:165] op_sel_hi:[1,0]
	v_mul_f32_e32 v112, v117, v117
	v_mul_f32_e32 v113, v119, v119
	v_cvt_pk_bf16_f32 v120, v124, v125
	v_pk_mul_f32 v[124:125], v[114:115], v[164:165] op_sel_hi:[1,0]
	v_fmac_f32_e32 v112, v116, v116
	v_fmac_f32_e32 v113, v118, v118
	v_add_f32_e32 v112, v112, v113
	v_mul_f32_e32 v113, v127, v127
	v_mul_f32_e32 v114, v125, v125
	v_fmac_f32_e32 v113, v126, v126
	v_fmac_f32_e32 v114, v124, v124
	v_add_f32_e32 v113, v113, v114
	v_add_f32_e32 v112, v112, v113
	v_add_f32_e32 v112, v161, v112
	v_mov_b32_e32 v113, v112
	v_mov_b32_e32 v251, v112
	s_nop 1
	v_permlane16_swap_b32_e32 v113, v251
	v_lshlrev_b64 v[166:167], 9, v[130:131]
	v_cvt_pk_bf16_f32 v122, v122, v123
	v_cvt_pk_bf16_f32 v123, v168, v169
	v_lshl_add_u64 v[164:165], v[146:147], 0, v[166:167]
	s_waitcnt lgkmcnt(0)
	v_add_f32_e32 v112, v113, v251
	v_mov_b32_e32 v113, v112
	v_mov_b32_e32 v251, v112
	s_nop 1
	v_permlane32_swap_b32_e32 v113, v251
	v_cvt_pk_bf16_f32 v114, v116, v117
	v_cvt_pk_bf16_f32 v115, v118, v119
	v_cvt_pk_bf16_f32 v116, v126, v127
	v_cvt_pk_bf16_f32 v117, v124, v125
	global_store_dwordx4 v[164:165], v[120:123], off
	global_store_dwordx4 v[164:165], v[114:117], off offset:256
	s_and_saveexec_b64 s[0:1], s[40:41]
	s_cbranch_execz .LBB0_596
	v_lshl_add_u64 v[114:115], v[130:131], 4, s[14:15]
	s_waitcnt lgkmcnt(0)
	v_add_f32_e32 v112, v113, v251
	global_store_dword v[114:115], v112, off

.LBB0_609:
	v_mul_f32_e32 v121, v121, v121
	v_mul_f32_e32 v117, v117, v117
	v_fmac_f32_e32 v121, v120, v120
	v_fmac_f32_e32 v117, v116, v116
	v_add_f32_e32 v116, v121, v117
	v_mul_f32_e32 v117, v119, v119
	v_mul_f32_e32 v115, v115, v115
	v_fmac_f32_e32 v117, v118, v118
	v_fmac_f32_e32 v115, v114, v114
	v_add_f32_e32 v114, v117, v115
	v_add_f32_e32 v114, v116, v114
	v_mul_f32_e32 v115, v165, v165
	v_mul_f32_e32 v116, v125, v125
	v_fmac_f32_e32 v115, v164, v164
	v_fmac_f32_e32 v116, v124, v124
	v_add_f32_e32 v115, v115, v116
	v_mul_f32_e32 v116, v127, v127
	v_mul_f32_e32 v117, v123, v123
	v_fmac_f32_e32 v116, v126, v126
	v_fmac_f32_e32 v117, v122, v122
	v_add_f32_e32 v116, v116, v117
	v_add_f32_e32 v115, v115, v116
	v_add_f32_e32 v114, v114, v115
	v_mov_b32_e32 v115, v114
	v_mov_b32_e32 v251, v114
	s_nop 1
	v_permlane16_swap_b32_e32 v115, v251
	s_waitcnt lgkmcnt(0)
	v_add_f32_e32 v114, v115, v251
	v_mov_b32_e32 v115, v114
	v_mov_b32_e32 v251, v114
	s_nop 1
	v_permlane32_swap_b32_e32 v115, v251
	s_and_saveexec_b64 s[0:1], s[40:41]
	s_cbranch_execz .LBB0_611
	v_lshlrev_b64 v[116:117], 5, v[112:113]
	v_lshl_add_u64 v[116:117], s[34:35], 0, v[116:117]
	v_lshl_add_u64 v[116:117], s[46:47], 2, v[116:117]
	s_lshl_b32 s64, s62, 2
	v_lshl_add_u64 v[116:117], v[116:117], 0, s[64:65]
	s_waitcnt lgkmcnt(0)
	v_add_f32_e32 v114, v115, v251
	global_store_dword v[116:117], v114, off

.LBB0_612:
	v_pk_mul_f32 v[110:111], v[110:111], v[162:163] op_sel_hi:[1,0]
	v_pk_mul_f32 v[108:109], v[108:109], v[162:163] op_sel_hi:[1,0]
	v_pk_mul_f32 v[116:117], v[106:107], v[162:163] op_sel_hi:[1,0]
	v_pk_mul_f32 v[106:107], v[104:105], v[162:163] op_sel_hi:[1,0]
	v_mul_f32_e32 v104, v109, v109
	v_mul_f32_e32 v105, v111, v111
	v_fmac_f32_e32 v104, v108, v108
	v_fmac_f32_e32 v105, v110, v110
	v_add_f32_e32 v104, v104, v105
	v_mul_f32_e32 v105, v107, v107
	v_mul_f32_e32 v118, v117, v117
	v_fmac_f32_e32 v105, v106, v106
	v_fmac_f32_e32 v118, v116, v116
	v_add_f32_e32 v105, v105, v118
	v_pk_mul_f32 v[102:103], v[102:103], v[162:163] op_sel_hi:[1,0]
	v_pk_mul_f32 v[100:101], v[100:101], v[162:163] op_sel_hi:[1,0]
	v_add_f32_e32 v118, v104, v105
	v_cvt_pk_bf16_f32 v105, v110, v111
	v_pk_mul_f32 v[110:111], v[96:97], v[162:163] op_sel_hi:[1,0]
	v_mul_f32_e32 v96, v101, v101
	v_mul_f32_e32 v97, v103, v103
	v_cvt_pk_bf16_f32 v104, v108, v109
	v_pk_mul_f32 v[108:109], v[98:99], v[162:163] op_sel_hi:[1,0]
	v_fmac_f32_e32 v96, v100, v100
	v_fmac_f32_e32 v97, v102, v102
	v_add_f32_e32 v96, v96, v97
	v_mul_f32_e32 v97, v111, v111
	v_mul_f32_e32 v98, v109, v109
	v_fmac_f32_e32 v97, v110, v110
	v_fmac_f32_e32 v98, v108, v108
	v_add_f32_e32 v97, v97, v98
	v_add_f32_e32 v96, v96, v97
	v_add_f32_e32 v96, v118, v96
	v_mov_b32_e32 v97, v96
	v_mov_b32_e32 v251, v96
	s_nop 1
	v_permlane16_swap_b32_e32 v97, v251
	s_waitcnt lgkmcnt(1)
	v_lshlrev_b64 v[114:115], 9, v[112:113]
	v_cvt_pk_bf16_f32 v106, v106, v107
	v_cvt_pk_bf16_f32 v107, v116, v117
	v_lshl_add_u64 v[114:115], v[146:147], 0, v[114:115]
	s_waitcnt lgkmcnt(0)
	v_add_f32_e32 v96, v97, v251
	v_mov_b32_e32 v97, v96
	v_mov_b32_e32 v251, v96
	s_nop 1
	v_permlane32_swap_b32_e32 v97, v251
	v_cvt_pk_bf16_f32 v98, v100, v101
	v_cvt_pk_bf16_f32 v99, v102, v103
	v_cvt_pk_bf16_f32 v100, v110, v111
	v_cvt_pk_bf16_f32 v101, v108, v109
	global_store_dwordx4 v[114:115], v[104:107], off
	global_store_dwordx4 v[114:115], v[98:101], off offset:256
	s_and_saveexec_b64 s[0:1], s[40:41]
	s_cbranch_execz .LBB0_614
	v_lshl_add_u64 v[98:99], v[112:113], 4, s[14:15]
	s_waitcnt lgkmcnt(0)
	v_add_f32_e32 v96, v97, v251
	global_store_dword v[98:99], v96, off

.LBB0_627:
	v_mul_f32_e32 v105, v105, v105
	v_mul_f32_e32 v101, v101, v101
	v_fmac_f32_e32 v105, v104, v104
	v_fmac_f32_e32 v101, v100, v100
	v_add_f32_e32 v100, v105, v101
	v_mul_f32_e32 v101, v103, v103
	v_mul_f32_e32 v99, v99, v99
	v_fmac_f32_e32 v101, v102, v102
	v_fmac_f32_e32 v99, v98, v98
	v_add_f32_e32 v98, v101, v99
	v_add_f32_e32 v98, v100, v98
	v_mul_f32_e32 v99, v113, v113
	v_mul_f32_e32 v100, v109, v109
	v_fmac_f32_e32 v99, v112, v112
	v_fmac_f32_e32 v100, v108, v108
	v_add_f32_e32 v99, v99, v100
	v_mul_f32_e32 v100, v111, v111
	v_mul_f32_e32 v101, v107, v107
	v_fmac_f32_e32 v100, v110, v110
	v_fmac_f32_e32 v101, v106, v106
	v_add_f32_e32 v100, v100, v101
	v_add_f32_e32 v99, v99, v100
	v_add_f32_e32 v98, v98, v99
	v_mov_b32_e32 v99, v98
	v_mov_b32_e32 v251, v98
	s_nop 1
	v_permlane16_swap_b32_e32 v99, v251
	s_waitcnt lgkmcnt(0)
	v_add_f32_e32 v98, v99, v251
	v_mov_b32_e32 v99, v98
	v_mov_b32_e32 v251, v98
	s_nop 1
	v_permlane32_swap_b32_e32 v99, v251
	s_and_saveexec_b64 s[0:1], s[40:41]
	s_cbranch_execz .LBB0_629
	v_lshlrev_b64 v[100:101], 5, v[96:97]
	v_lshl_add_u64 v[100:101], s[34:35], 0, v[100:101]
	v_lshl_add_u64 v[100:101], s[46:47], 2, v[100:101]
	s_lshl_b32 s64, s62, 2
	v_lshl_add_u64 v[100:101], v[100:101], 0, s[64:65]
	s_waitcnt lgkmcnt(0)
	v_add_f32_e32 v98, v99, v251
	global_store_dword v[100:101], v98, off

.LBB0_630:
	v_pk_mul_f32 v[94:95], v[94:95], v[160:161] op_sel_hi:[1,0]
	v_pk_mul_f32 v[92:93], v[92:93], v[160:161] op_sel_hi:[1,0]
	v_pk_mul_f32 v[100:101], v[90:91], v[160:161] op_sel_hi:[1,0]
	v_pk_mul_f32 v[90:91], v[88:89], v[160:161] op_sel_hi:[1,0]
	v_mul_f32_e32 v88, v93, v93
	v_mul_f32_e32 v89, v95, v95
	v_fmac_f32_e32 v88, v92, v92
	v_fmac_f32_e32 v89, v94, v94
	v_add_f32_e32 v88, v88, v89
	v_mul_f32_e32 v89, v91, v91
	v_mul_f32_e32 v102, v101, v101
	v_fmac_f32_e32 v89, v90, v90
	v_fmac_f32_e32 v102, v100, v100
	v_add_f32_e32 v89, v89, v102
	v_pk_mul_f32 v[86:87], v[86:87], v[160:161] op_sel_hi:[1,0]
	v_pk_mul_f32 v[84:85], v[84:85], v[160:161] op_sel_hi:[1,0]
	v_add_f32_e32 v102, v88, v89
	v_cvt_pk_bf16_f32 v89, v94, v95
	v_pk_mul_f32 v[94:95], v[80:81], v[160:161] op_sel_hi:[1,0]
	v_mul_f32_e32 v80, v85, v85
	v_mul_f32_e32 v81, v87, v87
	v_cvt_pk_bf16_f32 v88, v92, v93
	v_pk_mul_f32 v[92:93], v[82:83], v[160:161] op_sel_hi:[1,0]
	v_fmac_f32_e32 v80, v84, v84
	v_fmac_f32_e32 v81, v86, v86
	v_add_f32_e32 v80, v80, v81
	v_mul_f32_e32 v81, v95, v95
	v_mul_f32_e32 v82, v93, v93
	v_fmac_f32_e32 v81, v94, v94
	v_fmac_f32_e32 v82, v92, v92
	v_add_f32_e32 v81, v81, v82
	v_add_f32_e32 v80, v80, v81
	v_add_f32_e32 v80, v102, v80
	v_mov_b32_e32 v81, v80
	v_mov_b32_e32 v251, v80
	s_nop 1
	v_permlane16_swap_b32_e32 v81, v251
	s_waitcnt lgkmcnt(1)
	v_lshlrev_b64 v[98:99], 9, v[96:97]
	v_cvt_pk_bf16_f32 v90, v90, v91
	v_cvt_pk_bf16_f32 v91, v100, v101
	v_lshl_add_u64 v[98:99], v[146:147], 0, v[98:99]
	s_waitcnt lgkmcnt(0)
	v_add_f32_e32 v80, v81, v251
	v_mov_b32_e32 v81, v80
	v_mov_b32_e32 v251, v80
	s_nop 1
	v_permlane32_swap_b32_e32 v81, v251
	v_cvt_pk_bf16_f32 v82, v84, v85
	v_cvt_pk_bf16_f32 v83, v86, v87
	v_cvt_pk_bf16_f32 v84, v94, v95
	v_cvt_pk_bf16_f32 v85, v92, v93
	global_store_dwordx4 v[98:99], v[88:91], off
	global_store_dwordx4 v[98:99], v[82:85], off offset:256
	s_and_saveexec_b64 s[0:1], s[40:41]
	s_cbranch_execz .LBB0_632
	v_lshl_add_u64 v[82:83], v[96:97], 4, s[14:15]
	s_waitcnt lgkmcnt(0)
	v_add_f32_e32 v80, v81, v251
	global_store_dword v[82:83], v80, off

.LBB0_645:
	v_mul_f32_e32 v89, v89, v89
	v_mul_f32_e32 v85, v85, v85
	v_fmac_f32_e32 v89, v88, v88
	v_fmac_f32_e32 v85, v84, v84
	v_add_f32_e32 v84, v89, v85
	v_mul_f32_e32 v85, v87, v87
	v_mul_f32_e32 v83, v83, v83
	v_fmac_f32_e32 v85, v86, v86
	v_fmac_f32_e32 v83, v82, v82
	v_add_f32_e32 v82, v85, v83
	v_add_f32_e32 v82, v84, v82
	v_mul_f32_e32 v83, v97, v97
	v_mul_f32_e32 v84, v93, v93
	v_fmac_f32_e32 v83, v96, v96
	v_fmac_f32_e32 v84, v92, v92
	v_add_f32_e32 v83, v83, v84
	v_mul_f32_e32 v84, v95, v95
	v_mul_f32_e32 v85, v91, v91
	v_fmac_f32_e32 v84, v94, v94
	v_fmac_f32_e32 v85, v90, v90
	v_add_f32_e32 v84, v84, v85
	v_add_f32_e32 v83, v83, v84
	v_add_f32_e32 v82, v82, v83
	v_mov_b32_e32 v83, v82
	v_mov_b32_e32 v251, v82
	s_nop 1
	v_permlane16_swap_b32_e32 v83, v251
	s_waitcnt lgkmcnt(0)
	v_add_f32_e32 v82, v83, v251
	v_mov_b32_e32 v83, v82
	v_mov_b32_e32 v251, v82
	s_nop 1
	v_permlane32_swap_b32_e32 v83, v251
	s_and_saveexec_b64 s[0:1], s[40:41]
	s_cbranch_execz .LBB0_647
	v_lshlrev_b64 v[84:85], 5, v[80:81]
	v_lshl_add_u64 v[84:85], s[34:35], 0, v[84:85]
	v_lshl_add_u64 v[84:85], s[46:47], 2, v[84:85]
	s_lshl_b32 s64, s62, 2
	v_lshl_add_u64 v[84:85], v[84:85], 0, s[64:65]
	s_waitcnt lgkmcnt(0)
	v_add_f32_e32 v82, v83, v251
	global_store_dword v[84:85], v82, off

.LBB0_648:
	v_pk_mul_f32 v[78:79], v[78:79], v[158:159] op_sel_hi:[1,0]
	v_pk_mul_f32 v[76:77], v[76:77], v[158:159] op_sel_hi:[1,0]
	v_pk_mul_f32 v[84:85], v[74:75], v[158:159] op_sel_hi:[1,0]
	v_pk_mul_f32 v[74:75], v[72:73], v[158:159] op_sel_hi:[1,0]
	v_mul_f32_e32 v72, v77, v77
	v_mul_f32_e32 v73, v79, v79
	v_fmac_f32_e32 v72, v76, v76
	v_fmac_f32_e32 v73, v78, v78
	v_add_f32_e32 v72, v72, v73
	v_mul_f32_e32 v73, v75, v75
	v_mul_f32_e32 v86, v85, v85
	v_fmac_f32_e32 v73, v74, v74
	v_fmac_f32_e32 v86, v84, v84
	v_add_f32_e32 v73, v73, v86
	v_pk_mul_f32 v[70:71], v[70:71], v[158:159] op_sel_hi:[1,0]
	v_pk_mul_f32 v[68:69], v[68:69], v[158:159] op_sel_hi:[1,0]
	v_add_f32_e32 v86, v72, v73
	v_cvt_pk_bf16_f32 v73, v78, v79
	v_pk_mul_f32 v[78:79], v[64:65], v[158:159] op_sel_hi:[1,0]
	v_mul_f32_e32 v64, v69, v69
	v_mul_f32_e32 v65, v71, v71
	v_cvt_pk_bf16_f32 v72, v76, v77
	v_pk_mul_f32 v[76:77], v[66:67], v[158:159] op_sel_hi:[1,0]
	v_fmac_f32_e32 v64, v68, v68
	v_fmac_f32_e32 v65, v70, v70
	v_add_f32_e32 v64, v64, v65
	v_mul_f32_e32 v65, v79, v79
	v_mul_f32_e32 v66, v77, v77
	v_fmac_f32_e32 v65, v78, v78
	v_fmac_f32_e32 v66, v76, v76
	v_add_f32_e32 v65, v65, v66
	v_add_f32_e32 v64, v64, v65
	v_add_f32_e32 v64, v86, v64
	v_mov_b32_e32 v65, v64
	v_mov_b32_e32 v251, v64
	s_nop 1
	v_permlane16_swap_b32_e32 v65, v251
	s_waitcnt lgkmcnt(1)
	v_lshlrev_b64 v[82:83], 9, v[80:81]
	v_cvt_pk_bf16_f32 v74, v74, v75
	v_cvt_pk_bf16_f32 v75, v84, v85
	v_lshl_add_u64 v[82:83], v[146:147], 0, v[82:83]
	s_waitcnt lgkmcnt(0)
	v_add_f32_e32 v64, v65, v251
	v_mov_b32_e32 v65, v64
	v_mov_b32_e32 v251, v64
	s_nop 1
	v_permlane32_swap_b32_e32 v65, v251
	v_cvt_pk_bf16_f32 v66, v68, v69
	v_cvt_pk_bf16_f32 v67, v70, v71
	v_cvt_pk_bf16_f32 v68, v78, v79
	v_cvt_pk_bf16_f32 v69, v76, v77
	global_store_dwordx4 v[82:83], v[72:75], off
	global_store_dwordx4 v[82:83], v[66:69], off offset:256
	s_and_saveexec_b64 s[0:1], s[40:41]
	s_cbranch_execz .LBB0_650
	v_lshl_add_u64 v[66:67], v[80:81], 4, s[14:15]
	s_waitcnt lgkmcnt(0)
	v_add_f32_e32 v64, v65, v251
	global_store_dword v[66:67], v64, off

.LBB0_663:
	v_mul_f32_e32 v73, v73, v73
	v_mul_f32_e32 v69, v69, v69
	v_fmac_f32_e32 v73, v72, v72
	v_fmac_f32_e32 v69, v68, v68
	v_add_f32_e32 v68, v73, v69
	v_mul_f32_e32 v69, v71, v71
	v_mul_f32_e32 v67, v67, v67
	v_fmac_f32_e32 v69, v70, v70
	v_fmac_f32_e32 v67, v66, v66
	v_add_f32_e32 v66, v69, v67
	v_add_f32_e32 v66, v68, v66
	v_mul_f32_e32 v67, v81, v81
	v_mul_f32_e32 v68, v77, v77
	v_fmac_f32_e32 v67, v80, v80
	v_fmac_f32_e32 v68, v76, v76
	v_add_f32_e32 v67, v67, v68
	v_mul_f32_e32 v68, v79, v79
	v_mul_f32_e32 v69, v75, v75
	v_fmac_f32_e32 v68, v78, v78
	v_fmac_f32_e32 v69, v74, v74
	v_add_f32_e32 v68, v68, v69
	v_add_f32_e32 v67, v67, v68
	v_add_f32_e32 v66, v66, v67
	v_mov_b32_e32 v67, v66
	v_mov_b32_e32 v251, v66
	s_nop 1
	v_permlane16_swap_b32_e32 v67, v251
	s_waitcnt lgkmcnt(0)
	v_add_f32_e32 v66, v67, v251
	v_mov_b32_e32 v67, v66
	v_mov_b32_e32 v251, v66
	s_nop 1
	v_permlane32_swap_b32_e32 v67, v251
	s_and_saveexec_b64 s[0:1], s[40:41]
	s_cbranch_execz .LBB0_665
	v_lshlrev_b64 v[68:69], 5, v[64:65]
	v_lshl_add_u64 v[68:69], s[34:35], 0, v[68:69]
	v_lshl_add_u64 v[68:69], s[46:47], 2, v[68:69]
	s_lshl_b32 s64, s62, 2
	v_lshl_add_u64 v[68:69], v[68:69], 0, s[64:65]
	s_waitcnt lgkmcnt(0)
	v_add_f32_e32 v66, v67, v251
	global_store_dword v[68:69], v66, off

.LBB0_666:
	v_pk_mul_f32 v[62:63], v[62:63], v[156:157] op_sel_hi:[1,0]
	v_pk_mul_f32 v[60:61], v[60:61], v[156:157] op_sel_hi:[1,0]
	v_pk_mul_f32 v[68:69], v[58:59], v[156:157] op_sel_hi:[1,0]
	v_pk_mul_f32 v[58:59], v[56:57], v[156:157] op_sel_hi:[1,0]
	v_mul_f32_e32 v56, v61, v61
	v_mul_f32_e32 v57, v63, v63
	v_fmac_f32_e32 v56, v60, v60
	v_fmac_f32_e32 v57, v62, v62
	v_add_f32_e32 v56, v56, v57
	v_mul_f32_e32 v57, v59, v59
	v_mul_f32_e32 v70, v69, v69
	v_fmac_f32_e32 v57, v58, v58
	v_fmac_f32_e32 v70, v68, v68
	v_add_f32_e32 v57, v57, v70
	v_pk_mul_f32 v[54:55], v[54:55], v[156:157] op_sel_hi:[1,0]
	v_pk_mul_f32 v[52:53], v[52:53], v[156:157] op_sel_hi:[1,0]
	v_add_f32_e32 v70, v56, v57
	v_cvt_pk_bf16_f32 v57, v62, v63
	v_pk_mul_f32 v[62:63], v[48:49], v[156:157] op_sel_hi:[1,0]
	v_mul_f32_e32 v48, v53, v53
	v_mul_f32_e32 v49, v55, v55
	v_cvt_pk_bf16_f32 v56, v60, v61
	v_pk_mul_f32 v[60:61], v[50:51], v[156:157] op_sel_hi:[1,0]
	v_fmac_f32_e32 v48, v52, v52
	v_fmac_f32_e32 v49, v54, v54
	v_add_f32_e32 v48, v48, v49
	v_mul_f32_e32 v49, v63, v63
	v_mul_f32_e32 v50, v61, v61
	v_fmac_f32_e32 v49, v62, v62
	v_fmac_f32_e32 v50, v60, v60
	v_add_f32_e32 v49, v49, v50
	v_add_f32_e32 v48, v48, v49
	v_add_f32_e32 v48, v70, v48
	v_mov_b32_e32 v49, v48
	v_mov_b32_e32 v251, v48
	s_nop 1
	v_permlane16_swap_b32_e32 v49, v251
	s_waitcnt lgkmcnt(1)
	v_lshlrev_b64 v[66:67], 9, v[64:65]
	v_cvt_pk_bf16_f32 v58, v58, v59
	v_cvt_pk_bf16_f32 v59, v68, v69
	v_lshl_add_u64 v[66:67], v[146:147], 0, v[66:67]
	s_waitcnt lgkmcnt(0)
	v_add_f32_e32 v48, v49, v251
	v_mov_b32_e32 v49, v48
	v_mov_b32_e32 v251, v48
	s_nop 1
	v_permlane32_swap_b32_e32 v49, v251
	v_cvt_pk_bf16_f32 v50, v52, v53
	v_cvt_pk_bf16_f32 v51, v54, v55
	v_cvt_pk_bf16_f32 v52, v62, v63
	v_cvt_pk_bf16_f32 v53, v60, v61
	global_store_dwordx4 v[66:67], v[56:59], off
	global_store_dwordx4 v[66:67], v[50:53], off offset:256
	s_and_saveexec_b64 s[0:1], s[40:41]
	s_cbranch_execz .LBB0_668
	v_lshl_add_u64 v[50:51], v[64:65], 4, s[14:15]
	s_waitcnt lgkmcnt(0)
	v_add_f32_e32 v48, v49, v251
	global_store_dword v[50:51], v48, off

.LBB0_681:
	v_mul_f32_e32 v57, v57, v57
	v_mul_f32_e32 v53, v53, v53
	v_fmac_f32_e32 v57, v56, v56
	v_fmac_f32_e32 v53, v52, v52
	v_add_f32_e32 v52, v57, v53
	v_mul_f32_e32 v53, v55, v55
	v_mul_f32_e32 v51, v51, v51
	v_fmac_f32_e32 v53, v54, v54
	v_fmac_f32_e32 v51, v50, v50
	v_add_f32_e32 v50, v53, v51
	v_add_f32_e32 v50, v52, v50
	v_mul_f32_e32 v51, v65, v65
	v_mul_f32_e32 v52, v61, v61
	v_fmac_f32_e32 v51, v64, v64
	v_fmac_f32_e32 v52, v60, v60
	v_add_f32_e32 v51, v51, v52
	v_mul_f32_e32 v52, v63, v63
	v_mul_f32_e32 v53, v59, v59
	v_fmac_f32_e32 v52, v62, v62
	v_fmac_f32_e32 v53, v58, v58
	v_add_f32_e32 v52, v52, v53
	v_add_f32_e32 v51, v51, v52
	v_add_f32_e32 v50, v50, v51
	v_mov_b32_e32 v51, v50
	v_mov_b32_e32 v251, v50
	s_nop 1
	v_permlane16_swap_b32_e32 v51, v251
	s_waitcnt lgkmcnt(0)
	v_add_f32_e32 v50, v51, v251
	v_mov_b32_e32 v51, v50
	v_mov_b32_e32 v251, v50
	s_nop 1
	v_permlane32_swap_b32_e32 v51, v251
	s_and_saveexec_b64 s[0:1], s[40:41]
	s_cbranch_execz .LBB0_683
	v_lshlrev_b64 v[52:53], 5, v[48:49]
	v_lshl_add_u64 v[52:53], s[34:35], 0, v[52:53]
	v_lshl_add_u64 v[52:53], s[46:47], 2, v[52:53]
	s_lshl_b32 s64, s62, 2
	v_lshl_add_u64 v[52:53], v[52:53], 0, s[64:65]
	s_waitcnt lgkmcnt(0)
	v_add_f32_e32 v50, v51, v251
	global_store_dword v[52:53], v50, off

.LBB0_684:
	v_pk_mul_f32 v[46:47], v[46:47], v[154:155] op_sel_hi:[1,0]
	v_pk_mul_f32 v[44:45], v[44:45], v[154:155] op_sel_hi:[1,0]
	v_pk_mul_f32 v[52:53], v[42:43], v[154:155] op_sel_hi:[1,0]
	v_pk_mul_f32 v[42:43], v[40:41], v[154:155] op_sel_hi:[1,0]
	v_mul_f32_e32 v40, v45, v45
	v_mul_f32_e32 v41, v47, v47
	v_fmac_f32_e32 v40, v44, v44
	v_fmac_f32_e32 v41, v46, v46
	v_add_f32_e32 v40, v40, v41
	v_mul_f32_e32 v41, v43, v43
	v_mul_f32_e32 v54, v53, v53
	v_fmac_f32_e32 v41, v42, v42
	v_fmac_f32_e32 v54, v52, v52
	v_add_f32_e32 v41, v41, v54
	v_pk_mul_f32 v[38:39], v[38:39], v[154:155] op_sel_hi:[1,0]
	v_pk_mul_f32 v[36:37], v[36:37], v[154:155] op_sel_hi:[1,0]
	v_add_f32_e32 v54, v40, v41
	v_cvt_pk_bf16_f32 v41, v46, v47
	v_pk_mul_f32 v[46:47], v[32:33], v[154:155] op_sel_hi:[1,0]
	v_mul_f32_e32 v32, v37, v37
	v_mul_f32_e32 v33, v39, v39
	v_cvt_pk_bf16_f32 v40, v44, v45
	v_pk_mul_f32 v[44:45], v[34:35], v[154:155] op_sel_hi:[1,0]
	v_fmac_f32_e32 v32, v36, v36
	v_fmac_f32_e32 v33, v38, v38
	v_add_f32_e32 v32, v32, v33
	v_mul_f32_e32 v33, v47, v47
	v_mul_f32_e32 v34, v45, v45
	v_fmac_f32_e32 v33, v46, v46
	v_fmac_f32_e32 v34, v44, v44
	v_add_f32_e32 v33, v33, v34
	v_add_f32_e32 v32, v32, v33
	v_add_f32_e32 v32, v54, v32
	v_mov_b32_e32 v33, v32
	v_mov_b32_e32 v251, v32
	s_nop 1
	v_permlane16_swap_b32_e32 v33, v251
	s_waitcnt lgkmcnt(1)
	v_lshlrev_b64 v[50:51], 9, v[48:49]
	v_cvt_pk_bf16_f32 v42, v42, v43
	v_cvt_pk_bf16_f32 v43, v52, v53
	v_lshl_add_u64 v[50:51], v[146:147], 0, v[50:51]
	s_waitcnt lgkmcnt(0)
	v_add_f32_e32 v32, v33, v251
	v_mov_b32_e32 v33, v32
	v_mov_b32_e32 v251, v32
	s_nop 1
	v_permlane32_swap_b32_e32 v33, v251
	v_cvt_pk_bf16_f32 v34, v36, v37
	v_cvt_pk_bf16_f32 v35, v38, v39
	v_cvt_pk_bf16_f32 v36, v46, v47
	v_cvt_pk_bf16_f32 v37, v44, v45
	global_store_dwordx4 v[50:51], v[40:43], off
	global_store_dwordx4 v[50:51], v[34:37], off offset:256
	s_and_saveexec_b64 s[0:1], s[40:41]
	s_cbranch_execz .LBB0_686
	v_lshl_add_u64 v[34:35], v[48:49], 4, s[14:15]
	s_waitcnt lgkmcnt(0)
	v_add_f32_e32 v32, v33, v251
	global_store_dword v[34:35], v32, off

.LBB0_699:
	v_mul_f32_e32 v41, v41, v41
	v_mul_f32_e32 v37, v37, v37
	v_fmac_f32_e32 v41, v40, v40
	v_fmac_f32_e32 v37, v36, v36
	v_add_f32_e32 v36, v41, v37
	v_mul_f32_e32 v37, v39, v39
	v_mul_f32_e32 v35, v35, v35
	v_fmac_f32_e32 v37, v38, v38
	v_fmac_f32_e32 v35, v34, v34
	v_add_f32_e32 v34, v37, v35
	v_add_f32_e32 v34, v36, v34
	v_mul_f32_e32 v35, v49, v49
	v_mul_f32_e32 v36, v45, v45
	v_fmac_f32_e32 v35, v48, v48
	v_fmac_f32_e32 v36, v44, v44
	v_add_f32_e32 v35, v35, v36
	v_mul_f32_e32 v36, v47, v47
	v_mul_f32_e32 v37, v43, v43
	v_fmac_f32_e32 v36, v46, v46
	v_fmac_f32_e32 v37, v42, v42
	v_add_f32_e32 v36, v36, v37
	v_add_f32_e32 v35, v35, v36
	v_add_f32_e32 v34, v34, v35
	v_mov_b32_e32 v35, v34
	v_mov_b32_e32 v251, v34
	s_nop 1
	v_permlane16_swap_b32_e32 v35, v251
	s_waitcnt lgkmcnt(0)
	v_add_f32_e32 v34, v35, v251
	v_mov_b32_e32 v35, v34
	v_mov_b32_e32 v251, v34
	s_nop 1
	v_permlane32_swap_b32_e32 v35, v251
	s_and_saveexec_b64 s[0:1], s[40:41]
	s_cbranch_execz .LBB0_701
	v_lshlrev_b64 v[36:37], 5, v[32:33]
	v_lshl_add_u64 v[36:37], s[34:35], 0, v[36:37]
	v_lshl_add_u64 v[36:37], s[46:47], 2, v[36:37]
	s_lshl_b32 s64, s62, 2
	v_lshl_add_u64 v[36:37], v[36:37], 0, s[64:65]
	s_waitcnt lgkmcnt(0)
	v_add_f32_e32 v34, v35, v251
	global_store_dword v[36:37], v34, off

.LBB0_702:
	v_pk_mul_f32 v[30:31], v[30:31], v[152:153] op_sel_hi:[1,0]
	v_pk_mul_f32 v[28:29], v[28:29], v[152:153] op_sel_hi:[1,0]
	v_pk_mul_f32 v[36:37], v[26:27], v[152:153] op_sel_hi:[1,0]
	v_pk_mul_f32 v[26:27], v[24:25], v[152:153] op_sel_hi:[1,0]
	v_mul_f32_e32 v24, v29, v29
	v_mul_f32_e32 v25, v31, v31
	v_fmac_f32_e32 v24, v28, v28
	v_fmac_f32_e32 v25, v30, v30
	v_add_f32_e32 v24, v24, v25
	v_mul_f32_e32 v25, v27, v27
	v_mul_f32_e32 v38, v37, v37
	v_fmac_f32_e32 v25, v26, v26
	v_fmac_f32_e32 v38, v36, v36
	v_add_f32_e32 v25, v25, v38
	v_pk_mul_f32 v[22:23], v[22:23], v[152:153] op_sel_hi:[1,0]
	v_pk_mul_f32 v[20:21], v[20:21], v[152:153] op_sel_hi:[1,0]
	v_add_f32_e32 v38, v24, v25
	v_cvt_pk_bf16_f32 v25, v30, v31
	v_pk_mul_f32 v[30:31], v[16:17], v[152:153] op_sel_hi:[1,0]
	v_mul_f32_e32 v16, v21, v21
	v_mul_f32_e32 v17, v23, v23
	v_cvt_pk_bf16_f32 v24, v28, v29
	v_pk_mul_f32 v[28:29], v[18:19], v[152:153] op_sel_hi:[1,0]
	v_fmac_f32_e32 v16, v20, v20
	v_fmac_f32_e32 v17, v22, v22
	v_add_f32_e32 v16, v16, v17
	v_mul_f32_e32 v17, v31, v31
	v_mul_f32_e32 v18, v29, v29
	v_fmac_f32_e32 v17, v30, v30
	v_fmac_f32_e32 v18, v28, v28
	v_add_f32_e32 v17, v17, v18
	v_add_f32_e32 v16, v16, v17
	v_add_f32_e32 v16, v38, v16
	v_mov_b32_e32 v17, v16
	v_mov_b32_e32 v251, v16
	s_nop 1
	v_permlane16_swap_b32_e32 v17, v251
	s_waitcnt lgkmcnt(1)
	v_lshlrev_b64 v[34:35], 9, v[32:33]
	v_cvt_pk_bf16_f32 v26, v26, v27
	v_cvt_pk_bf16_f32 v27, v36, v37
	v_lshl_add_u64 v[34:35], v[146:147], 0, v[34:35]
	s_waitcnt lgkmcnt(0)
	v_add_f32_e32 v16, v17, v251
	v_mov_b32_e32 v17, v16
	v_mov_b32_e32 v251, v16
	s_nop 1
	v_permlane32_swap_b32_e32 v17, v251
	v_cvt_pk_bf16_f32 v18, v20, v21
	v_cvt_pk_bf16_f32 v19, v22, v23
	v_cvt_pk_bf16_f32 v20, v30, v31
	v_cvt_pk_bf16_f32 v21, v28, v29
	global_store_dwordx4 v[34:35], v[24:27], off
	global_store_dwordx4 v[34:35], v[18:21], off offset:256
	s_and_saveexec_b64 s[0:1], s[40:41]
	s_cbranch_execz .LBB0_704
	v_lshl_add_u64 v[18:19], v[32:33], 4, s[14:15]
	s_waitcnt lgkmcnt(0)
	v_add_f32_e32 v16, v17, v251
	global_store_dword v[18:19], v16, off

.LBB0_718:
	v_mul_f32_e32 v25, v25, v25
	v_mul_f32_e32 v21, v21, v21
	v_fmac_f32_e32 v25, v24, v24
	v_fmac_f32_e32 v21, v20, v20
	v_add_f32_e32 v20, v25, v21
	v_mul_f32_e32 v21, v23, v23
	v_mul_f32_e32 v19, v19, v19
	v_fmac_f32_e32 v21, v22, v22
	v_fmac_f32_e32 v19, v18, v18
	v_add_f32_e32 v18, v21, v19
	v_add_f32_e32 v18, v20, v18
	v_mul_f32_e32 v19, v33, v33
	v_mul_f32_e32 v20, v29, v29
	v_fmac_f32_e32 v19, v32, v32
	v_fmac_f32_e32 v20, v28, v28
	v_add_f32_e32 v19, v19, v20
	v_mul_f32_e32 v20, v31, v31
	v_mul_f32_e32 v21, v27, v27
	v_fmac_f32_e32 v20, v30, v30
	v_fmac_f32_e32 v21, v26, v26
	v_add_f32_e32 v20, v20, v21
	v_add_f32_e32 v19, v19, v20
	v_add_f32_e32 v18, v18, v19
	v_mov_b32_e32 v19, v18
	v_mov_b32_e32 v251, v18
	s_nop 1
	v_permlane16_swap_b32_e32 v19, v251
	s_waitcnt lgkmcnt(0)
	v_add_f32_e32 v18, v19, v251
	v_mov_b32_e32 v19, v18
	v_mov_b32_e32 v251, v18
	s_nop 1
	v_permlane32_swap_b32_e32 v19, v251
	s_and_saveexec_b64 s[0:1], s[40:41]
	s_cbranch_execz .LBB0_720
	v_lshlrev_b64 v[20:21], 5, v[16:17]
	v_lshl_add_u64 v[20:21], s[34:35], 0, v[20:21]
	v_lshl_add_u64 v[20:21], s[46:47], 2, v[20:21]
	s_lshl_b32 s64, s62, 2
	v_lshl_add_u64 v[20:21], v[20:21], 0, s[64:65]
	s_waitcnt lgkmcnt(0)
	v_add_f32_e32 v18, v19, v251
	global_store_dword v[20:21], v18, off

.LBB0_721:
	v_pk_mul_f32 v[14:15], v[14:15], v[128:129] op_sel_hi:[1,0]
	v_pk_mul_f32 v[12:13], v[12:13], v[128:129] op_sel_hi:[1,0]
	v_pk_mul_f32 v[20:21], v[10:11], v[128:129] op_sel_hi:[1,0]
	v_pk_mul_f32 v[10:11], v[8:9], v[128:129] op_sel_hi:[1,0]
	v_mul_f32_e32 v8, v13, v13
	v_mul_f32_e32 v9, v15, v15
	v_fmac_f32_e32 v8, v12, v12
	v_fmac_f32_e32 v9, v14, v14
	v_add_f32_e32 v8, v8, v9
	v_mul_f32_e32 v9, v11, v11
	v_mul_f32_e32 v22, v21, v21
	v_fmac_f32_e32 v9, v10, v10
	v_fmac_f32_e32 v22, v20, v20
	v_add_f32_e32 v9, v9, v22
	v_pk_mul_f32 v[6:7], v[6:7], v[128:129] op_sel_hi:[1,0]
	v_pk_mul_f32 v[4:5], v[4:5], v[128:129] op_sel_hi:[1,0]
	v_add_f32_e32 v22, v8, v9
	v_cvt_pk_bf16_f32 v9, v14, v15
	v_pk_mul_f32 v[14:15], v[0:1], v[128:129] op_sel_hi:[1,0]
	v_mul_f32_e32 v0, v5, v5
	v_mul_f32_e32 v1, v7, v7
	v_cvt_pk_bf16_f32 v8, v12, v13
	v_pk_mul_f32 v[12:13], v[2:3], v[128:129] op_sel_hi:[1,0]
	v_fmac_f32_e32 v0, v4, v4
	v_fmac_f32_e32 v1, v6, v6
	v_add_f32_e32 v0, v0, v1
	v_mul_f32_e32 v1, v15, v15
	v_mul_f32_e32 v2, v13, v13
	v_fmac_f32_e32 v1, v14, v14
	v_fmac_f32_e32 v2, v12, v12
	v_add_f32_e32 v1, v1, v2
	v_add_f32_e32 v0, v0, v1
	v_add_f32_e32 v0, v22, v0
	v_mov_b32_e32 v1, v0
	v_mov_b32_e32 v251, v0
	s_nop 1
	v_permlane16_swap_b32_e32 v1, v251
	s_waitcnt lgkmcnt(1)
	v_lshlrev_b64 v[18:19], 9, v[16:17]
	v_cvt_pk_bf16_f32 v10, v10, v11
	v_cvt_pk_bf16_f32 v11, v20, v21
	v_lshl_add_u64 v[18:19], v[146:147], 0, v[18:19]
	s_waitcnt lgkmcnt(0)
	v_add_f32_e32 v0, v1, v251
	v_mov_b32_e32 v1, v0
	v_mov_b32_e32 v251, v0
	s_nop 1
	v_permlane32_swap_b32_e32 v1, v251
	v_cvt_pk_bf16_f32 v2, v4, v5
	v_cvt_pk_bf16_f32 v3, v6, v7
	v_cvt_pk_bf16_f32 v4, v14, v15
	v_cvt_pk_bf16_f32 v5, v12, v13
	global_store_dwordx4 v[18:19], v[8:11], off
	global_store_dwordx4 v[18:19], v[2:5], off offset:256
	s_and_saveexec_b64 s[0:1], s[40:41]
	s_cbranch_execz .LBB0_723
	v_lshl_add_u64 v[2:3], v[16:17], 4, s[14:15]
	s_waitcnt lgkmcnt(0)
	v_add_f32_e32 v0, v1, v251
	global_store_dword v[2:3], v0, off
